# retd: LDS fragment reads software-pipelined one k-group ahead of the MFMAs; context-GEMM epilogue: residual/gate loads issued before the LDS reduction, reduction reads batched
# speedup vs baseline: 1.0138x; 1.0030x over previous
.LBB0_262:
	v_add_u32_e32 v52, s41, v39
	v_add_u32_e32 v53, s40, v39
	ds_read_b64_tr_b16 v[18:19], v52 offset:36864
	ds_read_b64_tr_b16 v[20:21], v52 offset:39168
	ds_read_b64_tr_b16 v[24:25], v53 offset:2304
	ds_read_b64_tr_b16 v[22:23], v53
	ds_read_b64_tr_b16 v[26:27], v53 offset:32
	ds_read_b64_tr_b16 v[28:29], v53 offset:2336
	ds_read_b64_tr_b16 v[40:41], v53 offset:64
	ds_read_b64_tr_b16 v[42:43], v53 offset:2368
	ds_read_b64_tr_b16 v[44:45], v53 offset:96
	ds_read_b64_tr_b16 v[46:47], v53 offset:2400
	s_waitcnt lgkmcnt(6)
	v_mfma_f32_16x16x32_bf16 v[22:25], v[18:21], v[22:25], 0
	s_ashr_i32 s23, s22, 31
	s_lshl_b32 s16, s100, 1
	s_lshl_b64 s[46:47], s[22:23], 14
	s_waitcnt lgkmcnt(4)
	v_mfma_f32_16x16x32_bf16 v[26:29], v[18:21], v[26:29], 0
	ds_read_b64_tr_b16 v[54:55], v52 offset:41472
	ds_read_b64_tr_b16 v[56:57], v52 offset:43776
	ds_read_b64_tr_b16 v[58:59], v53 offset:4608
	ds_read_b64_tr_b16 v[60:61], v53 offset:6912
	ds_read_b64_tr_b16 v[62:63], v53 offset:4640
	ds_read_b64_tr_b16 v[64:65], v53 offset:6944
	ds_read_b64_tr_b16 v[66:67], v53 offset:4672
	ds_read_b64_tr_b16 v[68:69], v53 offset:6976
	ds_read_b64_tr_b16 v[70:71], v53 offset:4704
	ds_read_b64_tr_b16 v[72:73], v53 offset:7008
	s_add_i32 s22, s22, s16
	s_lshl_b32 s16, s100, 5
	s_add_i32 s43, s43, s16
	s_waitcnt lgkmcnt(12)
	v_mfma_f32_16x16x32_bf16 v[40:43], v[18:21], v[40:43], 0
	s_lshl_b32 s16, s100, 6
	s_add_i32 s42, s42, s16
	s_andn2_b64 vcc, exec, s[26:27]
	s_waitcnt lgkmcnt(10)
	v_mfma_f32_16x16x32_bf16 v[18:21], v[18:21], v[44:47], 0
	s_waitcnt lgkmcnt(6)
	v_mfma_f32_16x16x32_bf16 v[22:25], v[54:57], v[58:61], v[22:25]
	s_waitcnt lgkmcnt(4)
	v_mfma_f32_16x16x32_bf16 v[26:29], v[54:57], v[62:65], v[26:29]
	ds_read_b64_tr_b16 v[74:75], v52 offset:46080
	ds_read_b64_tr_b16 v[76:77], v52 offset:48384
	ds_read_b64_tr_b16 v[78:79], v53 offset:9216
	ds_read_b64_tr_b16 v[80:81], v53 offset:11520
	ds_read_b64_tr_b16 v[82:83], v53 offset:9248
	ds_read_b64_tr_b16 v[84:85], v53 offset:11552
	ds_read_b64_tr_b16 v[86:87], v53 offset:9280
	ds_read_b64_tr_b16 v[88:89], v53 offset:11584
	ds_read_b64_tr_b16 v[90:91], v53 offset:9312
	ds_read_b64_tr_b16 v[92:93], v53 offset:11616
	s_waitcnt lgkmcnt(12)
	v_mfma_f32_16x16x32_bf16 v[40:43], v[54:57], v[66:69], v[40:43]
	s_waitcnt lgkmcnt(10)
	v_mfma_f32_16x16x32_bf16 v[18:21], v[54:57], v[70:73], v[18:21]
	s_waitcnt lgkmcnt(6)
	v_mfma_f32_16x16x32_bf16 v[22:25], v[74:77], v[78:81], v[22:25]
	s_waitcnt lgkmcnt(4)
	v_mfma_f32_16x16x32_bf16 v[26:29], v[74:77], v[82:85], v[26:29]
	ds_read_b64_tr_b16 v[94:95], v52 offset:50688
	ds_read_b64_tr_b16 v[96:97], v52 offset:52992
	ds_read_b64_tr_b16 v[98:99], v53 offset:13824
	ds_read_b64_tr_b16 v[100:101], v53 offset:16128
	ds_read_b64_tr_b16 v[102:103], v53 offset:13856
	ds_read_b64_tr_b16 v[104:105], v53 offset:16160
	ds_read_b64_tr_b16 v[106:107], v53 offset:13888
	ds_read_b64_tr_b16 v[108:109], v53 offset:16192
	ds_read_b64_tr_b16 v[110:111], v53 offset:13920
	ds_read_b64_tr_b16 v[112:113], v53 offset:16224
	s_waitcnt lgkmcnt(12)
	v_mfma_f32_16x16x32_bf16 v[40:43], v[74:77], v[86:89], v[40:43]
	s_waitcnt lgkmcnt(10)
	v_mfma_f32_16x16x32_bf16 v[18:21], v[74:77], v[90:93], v[18:21]
	s_waitcnt lgkmcnt(6)
	v_mfma_f32_16x16x32_bf16 v[22:25], v[94:97], v[98:101], v[22:25]
	s_waitcnt lgkmcnt(4)
	v_mfma_f32_16x16x32_bf16 v[26:29], v[94:97], v[102:105], v[26:29]
	s_waitcnt lgkmcnt(2)
	v_mfma_f32_16x16x32_bf16 v[40:43], v[94:97], v[106:109], v[40:43]
	s_waitcnt lgkmcnt(0)
	v_mfma_f32_16x16x32_bf16 v[18:21], v[94:97], v[110:113], v[18:21]
	v_lshl_add_u64 v[44:45], v[34:35], 0, s[46:47]
	global_store_dword v[44:45], v22, off
	global_store_dword v[44:45], v23, off offset:256
	global_store_dword v[44:45], v24, off offset:512
	global_store_dword v[44:45], v25, off offset:768
	global_store_dword v[44:45], v26, off offset:64
	global_store_dword v[44:45], v27, off offset:320
	global_store_dword v[44:45], v28, off offset:576
	global_store_dword v[44:45], v29, off offset:832
	global_store_dword v[44:45], v40, off offset:128
	global_store_dword v[44:45], v41, off offset:384
	global_store_dword v[44:45], v42, off offset:640
	global_store_dword v[44:45], v43, off offset:896
	global_store_dword v[44:45], v18, off offset:192
	global_store_dword v[44:45], v19, off offset:448
	global_store_dword v[44:45], v20, off offset:704
	global_store_dword v[44:45], v21, off offset:960
	s_barrier
	s_cbranch_vccz .LBB0_259

.Lmy_ctx_done:
	v_add_u32_e32 v0, s20, v53
	ds_write_b128 v0, v[30:33]
	ds_write_b128 v0, v[26:29] offset:1024
	ds_write_b128 v0, v[22:25] offset:2048
	ds_write_b128 v0, v[18:21] offset:3072
	ds_write_b128 v0, v[14:17] offset:4096
	ds_write_b128 v0, v[10:13] offset:5120
	ds_write_b128 v0, v[6:9] offset:6144
	ds_write_b128 v0, v[2:5] offset:7168
	s_waitcnt lgkmcnt(0)
	s_barrier
	v_or_b32_e32 v0, s28, v57
	v_lshlrev_b32_e32 v0, 2, v0
	v_mov_b32_e32 v143, v142
	s_add_i32 s21, s21, s96
	v_add_u32_e32 v116, s29, v56
	v_ashrrev_i32_e32 v117, 31, v116
	v_lshlrev_b64 v[116:117], 12, v[116:117]
	v_lshl_add_u64 v[118:119], s[48:49], 0, v[116:117]
	v_lshl_add_u64 v[116:117], s[2:3], 0, v[116:117]
	v_lshl_add_u64 v[116:117], v[116:117], 0, v[0:1]
	v_lshl_add_u64 v[14:15], v[118:119], 0, v[0:1]
	global_load_dwordx4 v[108:111], v[116:117], off
	global_load_dwordx4 v[112:115], v0, s[10:11]
	ds_read_b128 v[2:5], v54
	ds_read_b128 v[6:9], v55 offset:8192
	ds_read_b128 v[120:123], v55 offset:16384
	ds_read_b128 v[124:127], v55 offset:24576
	ds_read_b128 v[128:131], v55 offset:32768
	s_cmpk_gt_i32 s21, 0xff
	s_waitcnt lgkmcnt(3)
	v_pk_add_f32 v[8:9], v[4:5], v[8:9]
	v_pk_add_f32 v[6:7], v[2:3], v[6:7]
	s_waitcnt lgkmcnt(2)
	v_pk_add_f32 v[8:9], v[8:9], v[122:123]
	v_pk_add_f32 v[6:7], v[6:7], v[120:121]
	s_waitcnt lgkmcnt(1)
	v_pk_add_f32 v[8:9], v[8:9], v[126:127]
	v_pk_add_f32 v[6:7], v[6:7], v[124:125]
	s_waitcnt lgkmcnt(0)
	v_pk_add_f32 v[8:9], v[8:9], v[130:131]
	v_pk_add_f32 v[6:7], v[6:7], v[128:129]
	ds_read_b128 v[120:123], v55 offset:40960
	ds_read_b128 v[124:127], v55 offset:49152
	ds_read_b128 v[128:131], v55 offset:57344
	s_waitcnt lgkmcnt(2)
	v_pk_add_f32 v[8:9], v[8:9], v[122:123]
	v_pk_add_f32 v[6:7], v[6:7], v[120:121]
	s_waitcnt lgkmcnt(1)
	v_pk_add_f32 v[8:9], v[8:9], v[126:127]
	v_pk_add_f32 v[6:7], v[6:7], v[124:125]
	s_waitcnt lgkmcnt(0)
	v_pk_add_f32 v[12:13], v[6:7], v[128:129]
	v_pk_add_f32 v[10:11], v[8:9], v[130:131]
	s_waitcnt vmcnt(0)
	v_pk_mul_f32 v[6:7], v[12:13], v[112:113]
	v_pk_mul_f32 v[8:9], v[10:11], v[114:115]
	v_pk_fma_f32 v[2:3], v[38:39], v[6:7], v[108:109]
	v_add_co_u32_e32 v6, vcc, 0x8000000, v14
	v_pk_fma_f32 v[4:5], v[142:143], v[8:9], v[110:111]
	s_nop 0
	v_addc_co_u32_e32 v7, vcc, 0, v15, vcc
	global_store_dwordx4 v[6:7], v[2:5], off
	s_barrier
	s_cbranch_scc0 .LBB0_722
